# attention: incremental K pointers + SALU m0 for next-tile DMA issue; softmax in-place scalar sub/exp/sum/cvt without shuffles; PV via ds_read_b64 direct operand placement
# speedup vs baseline: 1.0086x; 1.0086x over previous
; #define LAS __attribute__((address_space(3)))
; DI void gload_lds16(const void* g, LAS char* l) { __builtin_amdgcn_global_load_lds((const unsigned*)g, (LAS unsigned*)l, 16, 0, 0); }
; DI void phase_attn(const Params& p, int l, LAS char* lds) {
;     ...
;         const int unit = k * G + ((k & 1) ? (G - 1 - (int)blockIdx.x) : (int)blockIdx.x);
;         if (unit >= NUNITS) continue;
;         const int qt = 32 - unit / 64, bh = unit & 63, b = bh >> 3, hd = bh & 7;
;         const int q0w = qt * 128 + w * 32;
;         const int nkt = (2 * qt + 2 < 65) ? 2 * qt + 2 : 65;
;         bf16x8 qf[6];
;         {
;             const int tq = (q0w + qi < LSEQ) ? q0w + qi : LSEQ - 1;
;             const bf16_t* qp = Q + ((size_t)(b * LSEQ + tq)) * 768 + hd * 96 + 8 * hh;
; #pragma unroll
;             for (int s = 0; s < 6; ++s) qf[s] = *(const bf16x8*)(qp + 16 * s);
;         }
;         const bf16_t* Knb = Kn + (size_t)b * LSEQ * 512 + hd * 64;
;         const bf16_t* Krb = Kr + (size_t)b * LSEQ * 32;
;         const bf16_t* Vtb = Vt + (size_t)bh * 64 * LP;
;         auto issue = [&](int stage, int kt) {
;             LAS char* base = lds + stage * 20480 + w * 1024;
; #pragma unroll
;             for (int j = 0; j < 3; ++j) {
;                 int tk = kt * 64 + krow_[j]; tk = (tk < LSEQ) ? tk : LSEQ - 1;
;                 const bf16_t* src = (kc_[j] < 8) ? Knb + (size_t)tk * 512 + kc_[j] * 8 : Krb + (size_t)tk * 32 + (kc_[j] - 8) * 8;
;                 gload_lds16(src, base + j * 4096);
;             }
; #pragma unroll
;             for (int j = 0; j < 2; ++j) gload_lds16(Vtb + (size_t)vrow_[j] * LP + kt * 64 + vc_[j] * 8, base + 12288 + j * 4096);
;         };
;         f32x16 o0, o1;
; #pragma unroll
;         for (int r = 0; r < 16; ++r) { o0[r] = 0.f; o1[r] = 0.f; }
;         float m_run = -INFINITY, l_run = 0.f;
;         issue(0, 0);
.LBB0_282:
	s_bitcmp0_b32 s54, 0
	s_cselect_b32 s1, s2, s75
	s_add_i32 s0, s1, s0
	s_cmpk_gt_i32 s0, 0x83f
	s_cbranch_scc1 .LBB0_281
	s_ashr_i32 s1, s0, 31
	s_lshr_b32 s1, s1, 26
	s_add_i32 s1, s0, s1
	s_ashr_i32 s1, s1, 6
	s_sub_i32 s4, 0, s1
	s_sub_i32 s1, 32, s1
	v_lshl_add_u32 v123, s1, 7, v141
	v_or_b32_e32 v122, v123, v91
	s_bfe_u32 s5, s0, 0x30003
	v_cmp_gt_i32_e64 s[44:45], s25, v122
	s_and_b32 s8, s0, 63
	s_and_b32 s6, s0, 7
	s_lshl_b32 s0, s1, 1
	v_cndmask_b32_e64 v1, v169, v122, s[44:45]
	s_mul_i32 s50, s5, 0x1010
	s_add_i32 s7, s0, 2
	v_add_u32_e32 v1, s50, v1
	v_mov_b64_e32 v[2:3], s[12:13]
	s_movk_i32 s0, 0x600
	v_mad_i64_i32 v[2:3], s[0:1], v1, s0, v[2:3]
	s_lshl_b32 s5, s50, 10
	s_lshl_b32 s0, s6, 6
	s_lshl_b32 s9, s50, 6
	s_cmp_gt_u32 s4, 0xffffffdf
	s_cselect_b32 s1, s7, 0x41
	s_add_u32 s4, s11, s5
	s_mul_i32 s34, s6, 0xc0
	s_addc_u32 s5, s74, 0
	s_lshl_b32 s6, s6, 7
	s_add_u32 s4, s4, s6
	s_addc_u32 s5, s5, 0
	s_add_u32 s6, s72, s9
	v_lshl_add_u64 v[2:3], v[2:3], 0, s[34:35]
	s_addc_u32 s7, s73, 0
	v_lshl_add_u64 v[2:3], v[2:3], 0, v[148:149]
	v_lshl_add_u64 v[4:5], s[6:7], 0, v[92:93]
	global_load_dwordx4 v[66:69], v[2:3], off
	global_load_dwordx4 v[70:73], v[2:3], off offset:32
	global_load_dwordx4 v[74:77], v[2:3], off offset:64
	global_load_dwordx4 v[78:81], v[2:3], off offset:96
	global_load_dwordx4 v[82:85], v[2:3], off offset:128
	global_load_dwordx4 v[86:89], v[2:3], off offset:160
	v_lshl_add_u64 v[2:3], s[4:5], 0, v[94:95]
	v_lshl_add_u64 v[4:5], v[4:5], 0, v[110:111]
	v_lshl_add_u64 v[2:3], v[2:3], 0, v[108:109]
	v_lshl_add_u64 v[4:5], v[4:5], 0, s[36:37]
	v_readfirstlane_b32 s10, v140
	v_cndmask_b32_e64 v3, v5, v3, s[38:39]
	v_cndmask_b32_e64 v2, v4, v2, s[38:39]
	s_mov_b32 m0, s10
	v_lshl_add_u64 v[4:5], s[6:7], 0, v[96:97]
	global_load_lds_dwordx4 v[2:3], off
	v_lshl_add_u64 v[2:3], s[4:5], 0, v[98:99]
	v_lshl_add_u64 v[4:5], v[4:5], 0, v[114:115]
	v_add_u32_e32 v1, 0x1000, v140
	v_lshl_add_u64 v[2:3], v[2:3], 0, v[112:113]
	v_lshl_add_u64 v[4:5], v[4:5], 0, s[36:37]
	v_readfirstlane_b32 s10, v1
	v_cndmask_b32_e64 v3, v5, v3, s[40:41]
	v_cndmask_b32_e64 v2, v4, v2, s[40:41]
	s_mov_b32 m0, s10
	v_lshl_add_u64 v[4:5], s[6:7], 0, v[100:101]
	s_mul_i32 s8, s8, 0x84000
	global_load_lds_dwordx4 v[2:3], off
	v_lshl_add_u64 v[2:3], s[4:5], 0, v[102:103]
	v_lshl_add_u64 v[4:5], v[4:5], 0, v[118:119]
	v_add_u32_e32 v1, 0x2000, v140
	s_add_u32 s8, s76, s8
	v_lshl_add_u64 v[2:3], v[2:3], 0, v[116:117]
	v_lshl_add_u64 v[4:5], v[4:5], 0, s[36:37]
	v_readfirstlane_b32 s10, v1
	s_addc_u32 s9, s77, 0
	v_cndmask_b32_e64 v3, v5, v3, s[42:43]
	v_cndmask_b32_e64 v2, v4, v2, s[42:43]
	s_mov_b32 m0, s10
	v_add_u32_e32 v1, 0x3000, v140
	global_load_lds_dwordx4 v[2:3], off
	v_lshl_add_u64 v[2:3], s[8:9], 0, v[104:105]
	v_mov_b32_e32 v121, v149
	v_readfirstlane_b32 s10, v1
	v_add_u32_e32 v1, 0x4000, v140
	v_lshl_add_u64 v[124:125], v[2:3], 0, v[120:121]
	s_mov_b32 m0, s10
	v_lshl_add_u64 v[2:3], s[8:9], 0, v[106:107]
	v_readfirstlane_b32 s8, v1
	global_load_lds_dwordx4 v[124:125], off
	v_lshl_add_u64 v[126:127], v[2:3], 0, v[120:121]
	s_mov_b32 m0, s8
	v_mov_b32_e32 v14, v0
	global_load_lds_dwordx4 v[126:127], off
	v_mov_b32_e32 v15, v0
	v_mov_b32_e32 v1, v0
	v_mov_b32_e32 v2, v0
	v_mov_b32_e32 v3, v0
	v_mov_b32_e32 v4, v0
	v_mov_b32_e32 v5, v0
	v_mov_b32_e32 v6, v0
	v_mov_b32_e32 v7, v0
	v_mov_b32_e32 v8, v0
	v_mov_b32_e32 v9, v0
	v_mov_b32_e32 v10, v0
	v_mov_b32_e32 v11, v0
	v_mov_b32_e32 v12, v0
	v_mov_b32_e32 v13, v0
	v_mov_b64_e32 v[32:33], v[14:15]
	v_mov_b64_e32 v[30:31], v[12:13]
	v_mov_b64_e32 v[28:29], v[10:11]
	v_mov_b64_e32 v[26:27], v[8:9]
	v_mov_b64_e32 v[24:25], v[6:7]
	v_mov_b64_e32 v[22:23], v[4:5]
	v_mov_b64_e32 v[20:21], v[2:3]
	v_mov_b64_e32 v[18:19], v[0:1]
	v_mov_b64_e32 v[16:17], v[14:15]
	s_mov_b32 s10, 0x800000
	s_mov_b32 s23, 0
	s_mov_b32 s51, s35
	v_or_b32_e32 v121, 31, v123
	v_lshl_add_u64 v[128:129], s[6:7], 0, v[110:111]
	v_lshl_add_u64 v[130:131], s[4:5], 0, v[108:109]
	v_lshl_add_u64 v[132:133], s[6:7], 0, v[114:115]
	v_lshl_add_u64 v[134:135], s[4:5], 0, v[112:113]
	v_lshl_add_u64 v[136:137], s[6:7], 0, v[118:119]
	v_lshl_add_u64 v[138:139], s[4:5], 0, v[116:117]
	v_readfirstlane_b32 s100, v140
	v_mov_b32_e32 v34, v180
	v_ashrrev_i32_e32 v35, 31, v34
	v_lshlrev_b64 v[36:37], 10, v[34:35]
	v_lshlrev_b64 v[34:35], 6, v[34:35]
	v_lshl_add_u64 v[34:35], v[128:129], 0, v[34:35]
	v_lshl_add_u64 v[36:37], v[130:131], 0, v[36:37]
	v_lshl_add_u64 v[34:35], v[34:35], 0, s[36:37]
	v_cndmask_b32_e64 v209, v35, v37, s[38:39]
	v_cndmask_b32_e64 v208, v34, v36, s[38:39]
	v_mov_b32_e32 v214, 0x1000
	v_mov_b32_e32 v34, 0x10000
	v_cndmask_b32_e64 v214, v214, v34, s[38:39]
	v_mov_b32_e32 v215, 0
	v_mov_b32_e32 v34, v179
	v_ashrrev_i32_e32 v35, 31, v34
	v_lshlrev_b64 v[36:37], 10, v[34:35]
	v_lshlrev_b64 v[34:35], 6, v[34:35]
	v_lshl_add_u64 v[34:35], v[132:133], 0, v[34:35]
	v_lshl_add_u64 v[36:37], v[134:135], 0, v[36:37]
	v_lshl_add_u64 v[34:35], v[34:35], 0, s[36:37]
	v_cndmask_b32_e64 v211, v35, v37, s[40:41]
	v_cndmask_b32_e64 v210, v34, v36, s[40:41]
	v_mov_b32_e32 v216, 0x1000
	v_mov_b32_e32 v34, 0x10000
	v_cndmask_b32_e64 v216, v216, v34, s[40:41]
	v_mov_b32_e32 v217, 0
	v_mov_b32_e32 v34, v178
	v_ashrrev_i32_e32 v35, 31, v34
	v_lshlrev_b64 v[36:37], 10, v[34:35]
	v_lshlrev_b64 v[34:35], 6, v[34:35]
	v_lshl_add_u64 v[34:35], v[136:137], 0, v[34:35]
	v_lshl_add_u64 v[36:37], v[138:139], 0, v[36:37]
	v_lshl_add_u64 v[34:35], v[34:35], 0, s[36:37]
	v_cndmask_b32_e64 v213, v35, v37, s[42:43]
	v_cndmask_b32_e64 v212, v34, v36, s[42:43]
	v_mov_b32_e32 v218, 0x1000
	v_mov_b32_e32 v34, 0x10000
	v_cndmask_b32_e64 v218, v218, v34, s[42:43]
	v_mov_b32_e32 v219, 0
	v_mov_b32_e32 v182, 0xff800000
	v_mov_b32_e32 v181, 0
	v_mov_b64_e32 v[14:15], v[12:13]
	v_mov_b64_e32 v[12:13], v[10:11]
	v_mov_b64_e32 v[10:11], v[8:9]
	v_mov_b64_e32 v[8:9], v[6:7]
	v_mov_b64_e32 v[6:7], v[4:5]
	v_mov_b64_e32 v[4:5], v[2:3]
	v_mov_b64_e32 v[2:3], v[0:1]
	s_mov_b32 s4, 0
	s_waitcnt vmcnt(0)
; #define LAS __attribute__((address_space(3)))
; DI void gload_lds16(const void* g, LAS char* l) { __builtin_amdgcn_global_load_lds((const unsigned*)g, (LAS unsigned*)l, 16, 0, 0); }
; DI void phase_attn(const Params& p, int l, LAS char* lds) {
;     ...
;         auto issue = [&](int stage, int kt) {
;             LAS char* base = lds + stage * 20480 + w * 1024;
; #pragma unroll
;             for (int j = 0; j < 3; ++j) {
;                 int tk = kt * 64 + krow_[j]; tk = (tk < LSEQ) ? tk : LSEQ - 1;
;                 const bf16_t* src = (kc_[j] < 8) ? Knb + (size_t)tk * 512 + kc_[j] * 8 : Krb + (size_t)tk * 32 + (kc_[j] - 8) * 8;
;                 gload_lds16(src, base + j * 4096);
;             }
; #pragma unroll
;             for (int j = 0; j < 2; ++j) gload_lds16(Vtb + (size_t)vrow_[j] * LP + kt * 64 + vc_[j] * 8, base + 12288 + j * 4096);
;         };
;         f32x16 o0, o1;
; #pragma unroll
;         for (int r = 0; r < 16; ++r) { o0[r] = 0.f; o1[r] = 0.f; }
;         float m_run = -INFINITY, l_run = 0.f;
;         issue(0, 0);
;         for (int kt = 0; kt < nkt; ++kt) {
;             asm volatile("s_waitcnt vmcnt(0)" ::: "memory");
;             __syncthreads();
;             if (kt + 1 < nkt) issue((kt + 1) & 1, kt + 1);
;             if (kt * 64 > q0w + 31) continue;
.LBB0_284:
	s_waitcnt vmcnt(0)
	s_add_i32 s33, s4, 1
	s_cmp_ge_u32 s33, s1
	s_waitcnt lgkmcnt(0)
	s_barrier
	s_cbranch_scc1 .LBB0_287
	s_cmp_eq_u32 s33, 64
	s_cbranch_scc1 .Lat_slow
	s_bitcmp1_b32 s33, 0
	s_cselect_b32 s5, 0x5000, 0
	s_add_u32 s5, s5, s100
	s_mov_b32 m0, s5
	s_add_i32 s34, s23, 64
	global_load_lds_dwordx4 v[208:209], off
	s_add_u32 m0, s5, 0x1000
	v_lshl_add_u64 v[208:209], v[208:209], 0, v[214:215]
	global_load_lds_dwordx4 v[210:211], off
	s_add_u32 m0, s5, 0x2000
	v_lshl_add_u64 v[210:211], v[210:211], 0, v[216:217]
	global_load_lds_dwordx4 v[212:213], off
	s_lshl_b64 s[6:7], s[34:35], 1
	v_lshl_add_u64 v[212:213], v[212:213], 0, v[218:219]
	s_add_u32 m0, s5, 0x3000
	v_lshl_add_u64 v[34:35], v[124:125], 0, s[6:7]
	global_load_lds_dwordx4 v[34:35], off
	s_add_u32 m0, s5, 0x4000
	v_lshl_add_u64 v[34:35], v[126:127], 0, s[6:7]
	global_load_lds_dwordx4 v[34:35], off
	s_branch .Lat_issued
.Lat_slow:
	v_add_u32_e32 v34, s23, v180
	v_min_i32_e32 v34, 0x100f, v34
	s_bitcmp1_b32 s33, 0
	v_ashrrev_i32_e32 v35, 31, v34
	s_cselect_b32 s5, 0x5000, 0
	v_lshlrev_b64 v[36:37], 10, v[34:35]
	v_lshlrev_b64 v[34:35], 6, v[34:35]
	v_add_u32_e32 v1, s5, v140
	v_lshl_add_u64 v[34:35], v[128:129], 0, v[34:35]
	v_lshl_add_u64 v[36:37], v[130:131], 0, v[36:37]
	v_lshl_add_u64 v[34:35], v[34:35], 0, s[36:37]
	v_readfirstlane_b32 s5, v1
	v_cndmask_b32_e64 v35, v35, v37, s[38:39]
	v_cndmask_b32_e64 v34, v34, v36, s[38:39]
	s_mov_b32 m0, s5
	s_add_i32 s34, s23, 64
	global_load_lds_dwordx4 v[34:35], off
	v_add_u32_e32 v34, s23, v179
	v_min_i32_e32 v34, 0x100f, v34
	v_ashrrev_i32_e32 v35, 31, v34
	v_lshlrev_b64 v[36:37], 10, v[34:35]
	v_lshlrev_b64 v[34:35], 6, v[34:35]
	v_lshl_add_u64 v[34:35], v[132:133], 0, v[34:35]
	v_lshl_add_u64 v[36:37], v[134:135], 0, v[36:37]
	v_lshl_add_u64 v[34:35], v[34:35], 0, s[36:37]
	v_cndmask_b32_e64 v34, v34, v36, s[40:41]
	v_add_u32_e32 v36, 0x1000, v1
	v_cndmask_b32_e64 v35, v35, v37, s[40:41]
	v_readfirstlane_b32 s5, v36
	s_mov_b32 m0, s5
	s_lshl_b64 s[6:7], s[34:35], 1
	global_load_lds_dwordx4 v[34:35], off
	v_add_u32_e32 v34, s23, v178
	v_min_i32_e32 v34, 0x100f, v34
	v_ashrrev_i32_e32 v35, 31, v34
	v_lshlrev_b64 v[36:37], 10, v[34:35]
	v_lshlrev_b64 v[34:35], 6, v[34:35]
	v_lshl_add_u64 v[34:35], v[136:137], 0, v[34:35]
	v_lshl_add_u64 v[36:37], v[138:139], 0, v[36:37]
	v_lshl_add_u64 v[34:35], v[34:35], 0, s[36:37]
	v_cndmask_b32_e64 v34, v34, v36, s[42:43]
	v_add_u32_e32 v36, 0x2000, v1
	v_cndmask_b32_e64 v35, v35, v37, s[42:43]
	v_readfirstlane_b32 s5, v36
	v_add_u32_e32 v36, 0x3000, v1
	s_mov_b32 m0, s5
	v_readfirstlane_b32 s5, v36
	v_add_u32_e32 v1, 0x4000, v1
	global_load_lds_dwordx4 v[34:35], off
	v_lshl_add_u64 v[34:35], v[124:125], 0, s[6:7]
	s_mov_b32 m0, s5
	v_readfirstlane_b32 s5, v1
	global_load_lds_dwordx4 v[34:35], off
	v_lshl_add_u64 v[34:35], v[126:127], 0, s[6:7]
	s_mov_b32 m0, s5
	s_nop 0
	global_load_lds_dwordx4 v[34:35], off
.Lat_issued:
	v_cmp_le_i32_e32 vcc, s23, v121
	s_and_saveexec_b64 s[48:49], vcc
	s_cbranch_execnz .LBB0_288

; #define LAS __attribute__((address_space(3)))
; DI unsigned pk2(float lo, float hi) { f32x2 v = {lo, hi}; bf2_t r = __builtin_convertvector(v, bf2_t); return __builtin_bit_cast(unsigned, r); }
; DI void phase_attn(const Params& p, int l, LAS char* lds) {
;     ...
;             float ps = 0.f;
; #pragma unroll
;             for (int r = 0; r < 16; ++r) { s0[r] = __builtin_amdgcn_exp2f(s0[r] - m_new); s1[r] = __builtin_amdgcn_exp2f(s1[r] - m_new); ps += s0[r] + s1[r]; }
;             l_run += ps;
;             bf16x8 pf[2][2];
; #pragma unroll
;             for (int s2 = 0; s2 < 2; ++s2) {
;                 u32x4 a, c2;
; #pragma unroll
;                 for (int e = 0; e < 4; ++e) { a[e] = pk2(s0[8 * s2 + 2 * e], s0[8 * s2 + 2 * e + 1]); c2[e] = pk2(s1[8 * s2 + 2 * e], s1[8 * s2 + 2 * e + 1]); }
;                 pf[0][s2] = __builtin_bit_cast(bf16x8, a); pf[1][s2] = __builtin_bit_cast(bf16x8, c2);
;             }
;             LAS char* vs = st + 12288;
;             __builtin_amdgcn_s_setprio(0);
; #pragma unroll
;             for (int tl = 0; tl < 2; ++tl)
; #pragma unroll
;                 for (int s2 = 0; s2 < 2; ++s2) {
;                     const int c = 4 * tl + 2 * s2;
;                     const int p0 = ((c ^ vsw) << 4) + 8 * hh, p1 = (((c + 1) ^ vsw) << 4) + 8 * hh;
;                     const s16x4 a0 = *(LAS s16x4*)(vs + qi * 128 + p0), a1 = *(LAS s16x4*)(vs + qi * 128 + p1);
;                     const s16x4 b0 = *(LAS s16x4*)(vs + (qi + 32) * 128 + p0), b1 = *(LAS s16x4*)(vs + (qi + 32) * 128 + p1);
;                     const bf16x8 v0 = __builtin_shufflevector(a0, a1, 0, 1, 2, 3, 4, 5, 6, 7);
;                     const bf16x8 v1 = __builtin_shufflevector(b0, b1, 0, 1, 2, 3, 4, 5, 6, 7);
;                     o0 = __builtin_amdgcn_mfma_f32_32x32x16_bf16(v0, pf[tl][s2], o0, 0, 0, 0);
;                     o1 = __builtin_amdgcn_mfma_f32_32x32x16_bf16(v1, pf[tl][s2], o1, 0, 0, 0);
;                 }
.LBB0_292:
	v_sub_f32_e32 v34, v34, v182
	v_sub_f32_e32 v35, v35, v182
	v_sub_f32_e32 v36, v36, v182
	v_sub_f32_e32 v37, v37, v182
	v_sub_f32_e32 v38, v38, v182
	v_sub_f32_e32 v39, v39, v182
	v_sub_f32_e32 v40, v40, v182
	v_sub_f32_e32 v41, v41, v182
	v_sub_f32_e32 v42, v42, v182
	v_sub_f32_e32 v43, v43, v182
	v_sub_f32_e32 v44, v44, v182
	v_sub_f32_e32 v45, v45, v182
	v_sub_f32_e32 v46, v46, v182
	v_sub_f32_e32 v47, v47, v182
	v_sub_f32_e32 v48, v48, v182
	v_sub_f32_e32 v49, v49, v182
	v_sub_f32_e32 v50, v50, v182
	v_sub_f32_e32 v51, v51, v182
	v_sub_f32_e32 v52, v52, v182
	v_sub_f32_e32 v53, v53, v182
	v_sub_f32_e32 v54, v54, v182
	v_sub_f32_e32 v55, v55, v182
	v_sub_f32_e32 v56, v56, v182
	v_sub_f32_e32 v57, v57, v182
	v_sub_f32_e32 v58, v58, v182
	v_sub_f32_e32 v59, v59, v182
	v_sub_f32_e32 v60, v60, v182
	v_sub_f32_e32 v61, v61, v182
	v_sub_f32_e32 v62, v62, v182
	v_sub_f32_e32 v63, v63, v182
	v_sub_f32_e32 v64, v64, v182
	v_sub_f32_e32 v65, v65, v182
	v_exp_f32_e32 v34, v34
	v_exp_f32_e32 v35, v35
	v_exp_f32_e32 v36, v36
	v_exp_f32_e32 v37, v37
	v_exp_f32_e32 v38, v38
	v_exp_f32_e32 v39, v39
	v_exp_f32_e32 v40, v40
	v_exp_f32_e32 v41, v41
	v_exp_f32_e32 v42, v42
	v_exp_f32_e32 v43, v43
	v_exp_f32_e32 v44, v44
	v_exp_f32_e32 v45, v45
	v_exp_f32_e32 v46, v46
	v_exp_f32_e32 v47, v47
	v_exp_f32_e32 v48, v48
	v_exp_f32_e32 v49, v49
	v_exp_f32_e32 v50, v50
	v_exp_f32_e32 v51, v51
	v_exp_f32_e32 v52, v52
	v_exp_f32_e32 v53, v53
	v_exp_f32_e32 v54, v54
	v_exp_f32_e32 v55, v55
	v_exp_f32_e32 v56, v56
	v_exp_f32_e32 v57, v57
	v_exp_f32_e32 v58, v58
	v_exp_f32_e32 v59, v59
	v_exp_f32_e32 v60, v60
	v_exp_f32_e32 v61, v61
	v_exp_f32_e32 v62, v62
	v_exp_f32_e32 v63, v63
	v_exp_f32_e32 v64, v64
	v_exp_f32_e32 v65, v65
	v_add_f32_e32 v184, v34, v35
	v_add_f32_e32 v185, v50, v51
	v_add_f32_e32 v186, v36, v37
	v_add_f32_e32 v187, v52, v53
	v_add_f32_e32 v184, v184, v38
	v_add_f32_e32 v185, v185, v54
	v_add_f32_e32 v186, v186, v39
	v_add_f32_e32 v187, v187, v55
	v_add_f32_e32 v184, v184, v40
	v_add_f32_e32 v185, v185, v56
	v_add_f32_e32 v186, v186, v41
	v_add_f32_e32 v187, v187, v57
	v_add_f32_e32 v184, v184, v42
	v_add_f32_e32 v185, v185, v58
	v_add_f32_e32 v186, v186, v43
	v_add_f32_e32 v187, v187, v59
	v_add_f32_e32 v184, v184, v44
	v_add_f32_e32 v185, v185, v60
	v_add_f32_e32 v186, v186, v45
	v_add_f32_e32 v187, v187, v61
	v_add_f32_e32 v184, v184, v46
	v_add_f32_e32 v185, v185, v62
	v_add_f32_e32 v186, v186, v47
	v_add_f32_e32 v187, v187, v63
	v_add_f32_e32 v184, v184, v48
	v_add_f32_e32 v185, v185, v64
	v_add_f32_e32 v186, v186, v49
	v_add_f32_e32 v187, v187, v65
	v_add_f32_e32 v184, v184, v186
	v_add_f32_e32 v185, v185, v187
	v_add_u32_e32 v183, s34, v143
	v_add_u32_e32 v220, v183, v154
	v_add_u32_e32 v221, v183, v155
	v_add_u32_e32 v222, v183, v156
	v_add_u32_e32 v223, v183, v157
	v_add_u32_e32 v224, v183, v158
	v_add_u32_e32 v225, v183, v159
	v_add_u32_e32 v226, v183, v160
	v_add_u32_e32 v227, v183, v161
	v_add_f32_e32 v1, v184, v185
	v_cvt_pk_bf16_f32 v34, v34, v35
	v_cvt_pk_bf16_f32 v35, v36, v37
	v_cvt_pk_bf16_f32 v36, v38, v39
	v_cvt_pk_bf16_f32 v37, v40, v41
	v_cvt_pk_bf16_f32 v38, v42, v43
	v_cvt_pk_bf16_f32 v39, v44, v45
	v_cvt_pk_bf16_f32 v40, v46, v47
	v_cvt_pk_bf16_f32 v41, v48, v49
	v_cvt_pk_bf16_f32 v42, v50, v51
	v_cvt_pk_bf16_f32 v43, v52, v53
	v_cvt_pk_bf16_f32 v44, v54, v55
	v_cvt_pk_bf16_f32 v45, v56, v57
	v_cvt_pk_bf16_f32 v46, v58, v59
	v_cvt_pk_bf16_f32 v47, v60, v61
	v_cvt_pk_bf16_f32 v48, v62, v63
	v_cvt_pk_bf16_f32 v49, v64, v65
	v_add_f32_e32 v181, v181, v1
	s_setprio 0
	ds_read_b64 v[50:51], v220 offset:12288
	ds_read_b64 v[54:55], v220 offset:16384
	ds_read_b64 v[52:53], v221 offset:12288
	ds_read_b64 v[56:57], v221 offset:16384
	ds_read_b64 v[58:59], v222 offset:12288
	ds_read_b64 v[62:63], v222 offset:16384
	ds_read_b64 v[60:61], v223 offset:12288
	ds_read_b64 v[64:65], v223 offset:16384
	ds_read_b64 a[0:1], v224 offset:12288
	ds_read_b64 a[4:5], v224 offset:16384
	ds_read_b64 a[2:3], v225 offset:12288
	ds_read_b64 a[6:7], v225 offset:16384
	ds_read_b64 a[8:9], v226 offset:12288
	ds_read_b64 a[12:13], v226 offset:16384
	ds_read_b64 a[10:11], v227 offset:12288
	ds_read_b64 a[14:15], v227 offset:16384
	s_waitcnt lgkmcnt(12)
	v_mfma_f32_32x32x16_bf16 v[18:33], v[50:53], v[34:37], v[18:33]
	v_mfma_f32_32x32x16_bf16 v[2:17], v[54:57], v[34:37], v[2:17]
	s_waitcnt lgkmcnt(8)
	v_mfma_f32_32x32x16_bf16 v[18:33], v[58:61], v[38:41], v[18:33]
	v_mfma_f32_32x32x16_bf16 v[2:17], v[62:65], v[38:41], v[2:17]
	s_waitcnt lgkmcnt(4)
	v_mfma_f32_32x32x16_bf16 v[18:33], a[0:3], v[42:45], v[18:33]
	v_mfma_f32_32x32x16_bf16 v[2:17], a[4:7], v[42:45], v[2:17]
	s_waitcnt lgkmcnt(0)
	v_mfma_f32_32x32x16_bf16 v[18:33], a[8:11], v[46:49], v[18:33]
	v_mfma_f32_32x32x16_bf16 v[2:17], a[12:15], v[46:49], v[2:17]
	s_or_b64 exec, exec, s[48:49]
	s_add_i32 s23, s23, 64
	s_cmp_eq_u32 s1, s33
	s_cbranch_scc1 .LBB0_294
